# merge u-GEMM (K=512) loop also LDS-DMA double-buffered; parked sigmoid moved from LDS to 32 VGPRs to free the LDS stage
# speedup vs baseline: 1.0995x; 1.0136x over previous
.Lmgd_skip:
	ds_read_b128 v[236:239], v172 offset:32768
	ds_read_b128 v[244:247], v176 offset:32768
	ds_read_b128 v[248:251], v176 offset:36864
	ds_read_b128 v[240:243], v172 offset:36864
	s_waitcnt lgkmcnt(2)
	v_mfma_f32_32x32x16_bf16 v[50:65], v[236:239], v[244:247], v[50:65]
	s_waitcnt lgkmcnt(1)
	v_mfma_f32_32x32x16_bf16 v[34:49], v[236:239], v[248:251], v[34:49]
	ds_read_b128 v[236:239], v173 offset:32768
	s_waitcnt lgkmcnt(1)
	v_mfma_f32_32x32x16_bf16 v[18:33], v[240:243], v[244:247], v[18:33]
	ds_read_b128 v[244:247], v177 offset:32768
	v_mfma_f32_32x32x16_bf16 v[2:17], v[240:243], v[248:251], v[2:17]
	ds_read_b128 v[248:251], v177 offset:36864
	ds_read_b128 v[240:243], v173 offset:36864
	s_waitcnt lgkmcnt(2)
	v_mfma_f32_32x32x16_bf16 v[50:65], v[236:239], v[244:247], v[50:65]
	s_waitcnt lgkmcnt(1)
	v_mfma_f32_32x32x16_bf16 v[34:49], v[236:239], v[248:251], v[34:49]
	ds_read_b128 v[236:239], v174 offset:32768
	s_waitcnt lgkmcnt(1)
	v_mfma_f32_32x32x16_bf16 v[18:33], v[240:243], v[244:247], v[18:33]
	ds_read_b128 v[244:247], v178 offset:32768
	v_mfma_f32_32x32x16_bf16 v[2:17], v[240:243], v[248:251], v[2:17]
	ds_read_b128 v[248:251], v178 offset:36864
	ds_read_b128 v[240:243], v174 offset:36864
	s_waitcnt lgkmcnt(2)
	v_mfma_f32_32x32x16_bf16 v[50:65], v[236:239], v[244:247], v[50:65]
	s_waitcnt lgkmcnt(1)
	v_mfma_f32_32x32x16_bf16 v[34:49], v[236:239], v[248:251], v[34:49]
	ds_read_b128 v[236:239], v175 offset:32768
	s_waitcnt lgkmcnt(1)
	v_mfma_f32_32x32x16_bf16 v[18:33], v[240:243], v[244:247], v[18:33]
	ds_read_b128 v[244:247], v179 offset:32768
	v_mfma_f32_32x32x16_bf16 v[2:17], v[240:243], v[248:251], v[2:17]
	ds_read_b128 v[248:251], v179 offset:36864
	ds_read_b128 v[240:243], v175 offset:36864
	s_waitcnt lgkmcnt(2)
	v_mfma_f32_32x32x16_bf16 v[50:65], v[236:239], v[244:247], v[50:65]
	s_waitcnt lgkmcnt(1)
	v_mfma_f32_32x32x16_bf16 v[34:49], v[236:239], v[248:251], v[34:49]
	s_waitcnt lgkmcnt(0)
	v_mfma_f32_32x32x16_bf16 v[18:33], v[240:243], v[244:247], v[18:33]
	v_mfma_f32_32x32x16_bf16 v[2:17], v[240:243], v[248:251], v[2:17]
	s_waitcnt vmcnt(0)
	s_add_i32 s7, s7, 1
	s_cmp_lg_u32 s7, 8
	s_cbranch_scc1 .Lmgd_loop
	s_barrier
	s_nop 15
	s_nop 6
	v_mul_f32_e32 v0, 0xbfb8aa3b, v50
	v_exp_f32_e32 v50, v0
	v_mul_f32_e32 v0, 0xbfb8aa3b, v51
	v_exp_f32_e32 v51, v0
	v_mul_f32_e32 v52, 0xbfb8aa3b, v52
	v_mul_f32_e32 v53, 0xbfb8aa3b, v53
	v_exp_f32_e32 v52, v52
	v_pk_add_f32 v[50:51], v[50:51], 1.0 op_sel_hi:[1,0]
	v_exp_f32_e32 v53, v53
	v_div_scale_f32 v0, s[4:5], v51, v51, 1.0
	v_rcp_f32_e32 v156, v0
	v_div_scale_f32 v158, vcc, 1.0, v51, 1.0
	v_pk_add_f32 v[52:53], v[52:53], 1.0 op_sel_hi:[1,0]
	v_fma_f32 v159, -v0, v156, 1.0
	v_fmac_f32_e32 v156, v159, v156
	v_mul_f32_e32 v159, v158, v156
	v_fma_f32 v160, -v0, v159, v158
	v_fmac_f32_e32 v159, v160, v156
	v_fma_f32 v0, -v0, v159, v158
	v_div_scale_f32 v158, s[4:5], v50, v50, 1.0
	v_rcp_f32_e32 v160, v158
	v_div_fmas_f32 v0, v0, v156, v159
	v_div_fixup_f32 v0, v0, v51, 1.0
	v_mul_f32_e32 v34, 0xbfb8aa3b, v34
	v_fma_f32 v51, -v158, v160, 1.0
	v_fmac_f32_e32 v160, v51, v160
	v_div_scale_f32 v51, vcc, 1.0, v50, 1.0
	v_mul_f32_e32 v156, v51, v160
	v_fma_f32 v159, -v158, v156, v51
	v_fmac_f32_e32 v156, v159, v160
	v_fma_f32 v51, -v158, v156, v51
	v_div_scale_f32 v158, s[4:5], v53, v53, 1.0
	v_rcp_f32_e32 v159, v158
	v_div_fmas_f32 v51, v51, v160, v156
	v_div_fixup_f32 v50, v51, v50, 1.0
	v_cvt_pk_bf16_f32 v0, v50, v0
	v_fma_f32 v50, -v158, v159, 1.0
	v_fmac_f32_e32 v159, v50, v159
	v_div_scale_f32 v50, vcc, 1.0, v53, 1.0
	v_mul_f32_e32 v51, v50, v159
	v_fma_f32 v156, -v158, v51, v50
	v_fmac_f32_e32 v51, v156, v159
	v_div_scale_f32 v156, s[4:5], v52, v52, 1.0
	v_fma_f32 v50, -v158, v51, v50
	v_rcp_f32_e32 v158, v156
	v_div_fmas_f32 v50, v50, v159, v51
	v_div_fixup_f32 v53, v50, v53, 1.0
	v_div_scale_f32 v159, vcc, 1.0, v52, 1.0
	v_fma_f32 v50, -v156, v158, 1.0
	v_fmac_f32_e32 v158, v50, v158
	v_mul_f32_e32 v160, v159, v158
	v_fma_f32 v50, -v156, v160, v159
	v_fmac_f32_e32 v160, v50, v158
	v_mul_f32_e32 v50, 0xbfb8aa3b, v54
	v_mul_f32_e32 v51, 0xbfb8aa3b, v55
	v_exp_f32_e32 v50, v50
	v_exp_f32_e32 v51, v51
	v_fma_f32 v54, -v156, v160, v159
	v_div_fmas_f32 v54, v54, v158, v160
	v_div_fixup_f32 v52, v54, v52, 1.0
	v_pk_add_f32 v[50:51], v[50:51], 1.0 op_sel_hi:[1,0]
	v_cvt_pk_bf16_f32 v52, v52, v53
	v_div_scale_f32 v55, s[4:5], v51, v51, 1.0
	v_rcp_f32_e32 v156, v55
	v_mov_b32_e32 v215, v0
	v_mov_b32_e32 v216, v52
	v_div_scale_f32 v54, s[4:5], v50, v50, 1.0
	v_fma_f32 v0, -v55, v156, 1.0
	v_fmac_f32_e32 v156, v0, v156
	v_div_scale_f32 v0, vcc, 1.0, v51, 1.0
	v_mul_f32_e32 v52, v0, v156
	v_fma_f32 v53, -v55, v52, v0
	v_fmac_f32_e32 v52, v53, v156
	v_fma_f32 v0, -v55, v52, v0
	v_rcp_f32_e32 v55, v54
	v_div_fmas_f32 v0, v0, v156, v52
	v_mul_f32_e32 v52, 0xbfb8aa3b, v56
	v_mul_f32_e32 v53, 0xbfb8aa3b, v57
	v_div_fixup_f32 v0, v0, v51, 1.0
	v_fma_f32 v51, -v54, v55, 1.0
	v_exp_f32_e32 v52, v52
	v_exp_f32_e32 v53, v53
	v_fmac_f32_e32 v55, v51, v55
	v_div_scale_f32 v51, vcc, 1.0, v50, 1.0
	v_mul_f32_e32 v156, v51, v55
	v_fma_f32 v56, -v54, v156, v51
	v_fmac_f32_e32 v156, v56, v55
	v_pk_add_f32 v[52:53], v[52:53], 1.0 op_sel_hi:[1,0]
	v_fma_f32 v51, -v54, v156, v51
	v_div_scale_f32 v54, s[4:5], v53, v53, 1.0
	v_rcp_f32_e32 v56, v54
	v_div_fmas_f32 v51, v51, v55, v156
	v_div_fixup_f32 v50, v51, v50, 1.0
	v_cvt_pk_bf16_f32 v0, v50, v0
	v_fma_f32 v50, -v54, v56, 1.0
	v_fmac_f32_e32 v56, v50, v56
	v_div_scale_f32 v50, vcc, 1.0, v53, 1.0
	v_mul_f32_e32 v51, v50, v56
	v_fma_f32 v55, -v54, v51, v50
	v_fmac_f32_e32 v51, v55, v56
	v_fma_f32 v50, -v54, v51, v50
	v_div_scale_f32 v54, s[4:5], v52, v52, 1.0
	v_rcp_f32_e32 v55, v54
	v_div_fmas_f32 v50, v50, v56, v51
	v_div_fixup_f32 v53, v50, v53, 1.0
	v_div_scale_f32 v56, vcc, 1.0, v52, 1.0
	v_fma_f32 v50, -v54, v55, 1.0
	v_fmac_f32_e32 v55, v50, v55
	v_mul_f32_e32 v57, v56, v55
	v_fma_f32 v50, -v54, v57, v56
	v_fmac_f32_e32 v57, v50, v55
	v_mul_f32_e32 v50, 0xbfb8aa3b, v58
	v_mul_f32_e32 v51, 0xbfb8aa3b, v59
	v_exp_f32_e32 v50, v50
	v_exp_f32_e32 v51, v51
	v_fma_f32 v54, -v54, v57, v56
	v_div_fmas_f32 v54, v54, v55, v57
	v_div_fixup_f32 v52, v54, v52, 1.0
	v_pk_add_f32 v[50:51], v[50:51], 1.0 op_sel_hi:[1,0]
	v_cvt_pk_bf16_f32 v52, v52, v53
	v_div_scale_f32 v55, s[4:5], v51, v51, 1.0
	v_rcp_f32_e32 v56, v55
	v_mov_b32_e32 v217, v0
	v_mov_b32_e32 v218, v52
	v_div_scale_f32 v54, s[4:5], v50, v50, 1.0
	v_fma_f32 v0, -v55, v56, 1.0
	v_fmac_f32_e32 v56, v0, v56
	v_div_scale_f32 v0, vcc, 1.0, v51, 1.0
	v_mul_f32_e32 v52, v0, v56
	v_fma_f32 v53, -v55, v52, v0
	v_fmac_f32_e32 v52, v53, v56
	v_fma_f32 v0, -v55, v52, v0
	v_rcp_f32_e32 v55, v54
	v_div_fmas_f32 v0, v0, v56, v52
	v_mul_f32_e32 v52, 0xbfb8aa3b, v60
	v_mul_f32_e32 v53, 0xbfb8aa3b, v61
	v_div_fixup_f32 v0, v0, v51, 1.0
	v_fma_f32 v51, -v54, v55, 1.0
	v_exp_f32_e32 v52, v52
	v_exp_f32_e32 v53, v53
	v_fmac_f32_e32 v55, v51, v55
	v_div_scale_f32 v51, vcc, 1.0, v50, 1.0
	v_mul_f32_e32 v56, v51, v55
	v_fma_f32 v57, -v54, v56, v51
	v_fmac_f32_e32 v56, v57, v55
	v_pk_add_f32 v[52:53], v[52:53], 1.0 op_sel_hi:[1,0]
	v_fma_f32 v51, -v54, v56, v51
	v_div_scale_f32 v54, s[4:5], v53, v53, 1.0
	v_rcp_f32_e32 v57, v54
	v_div_fmas_f32 v51, v51, v55, v56
	v_div_fixup_f32 v50, v51, v50, 1.0
	v_cvt_pk_bf16_f32 v0, v50, v0
	v_fma_f32 v50, -v54, v57, 1.0
	v_fmac_f32_e32 v57, v50, v57
	v_div_scale_f32 v50, vcc, 1.0, v53, 1.0
	v_mul_f32_e32 v51, v50, v57
	v_fma_f32 v55, -v54, v51, v50
	v_fmac_f32_e32 v51, v55, v57
	v_fma_f32 v50, -v54, v51, v50
	v_div_scale_f32 v54, s[4:5], v52, v52, 1.0
	v_rcp_f32_e32 v55, v54
	v_div_fmas_f32 v50, v50, v57, v51
	v_div_fixup_f32 v53, v50, v53, 1.0
	v_div_scale_f32 v56, vcc, 1.0, v52, 1.0
	v_fma_f32 v50, -v54, v55, 1.0
	v_fmac_f32_e32 v55, v50, v55
	v_mul_f32_e32 v57, v56, v55
	v_fma_f32 v50, -v54, v57, v56
	v_fmac_f32_e32 v57, v50, v55
	v_mul_f32_e32 v50, 0xbfb8aa3b, v62
	v_mul_f32_e32 v51, 0xbfb8aa3b, v63
	v_exp_f32_e32 v50, v50
	v_exp_f32_e32 v51, v51
	v_fma_f32 v54, -v54, v57, v56
	v_div_fmas_f32 v54, v54, v55, v57
	v_div_fixup_f32 v52, v54, v52, 1.0
	v_pk_add_f32 v[50:51], v[50:51], 1.0 op_sel_hi:[1,0]
	v_cvt_pk_bf16_f32 v52, v52, v53
	v_div_scale_f32 v55, s[4:5], v51, v51, 1.0
	v_rcp_f32_e32 v56, v55
	v_mov_b32_e32 v219, v0
	v_mov_b32_e32 v220, v52
	v_div_scale_f32 v54, s[4:5], v50, v50, 1.0
	v_fma_f32 v0, -v55, v56, 1.0
	v_fmac_f32_e32 v56, v0, v56
	v_div_scale_f32 v0, vcc, 1.0, v51, 1.0
	v_mul_f32_e32 v52, v0, v56
	v_fma_f32 v53, -v55, v52, v0
	v_fmac_f32_e32 v52, v53, v56
	v_fma_f32 v0, -v55, v52, v0
	v_rcp_f32_e32 v55, v54
	v_div_fmas_f32 v0, v0, v56, v52
	v_mul_f32_e32 v52, 0xbfb8aa3b, v64
	v_mul_f32_e32 v53, 0xbfb8aa3b, v65
	v_div_fixup_f32 v0, v0, v51, 1.0
	v_fma_f32 v51, -v54, v55, 1.0
	v_exp_f32_e32 v52, v52
	v_exp_f32_e32 v53, v53
	v_fmac_f32_e32 v55, v51, v55
	v_div_scale_f32 v51, vcc, 1.0, v50, 1.0
	v_mul_f32_e32 v56, v51, v55
	v_fma_f32 v57, -v54, v56, v51
	v_fmac_f32_e32 v56, v57, v55
	v_pk_add_f32 v[52:53], v[52:53], 1.0 op_sel_hi:[1,0]
	v_fma_f32 v51, -v54, v56, v51
	v_div_scale_f32 v54, s[4:5], v53, v53, 1.0
	v_rcp_f32_e32 v57, v54
	v_div_fmas_f32 v51, v51, v55, v56
	v_div_fixup_f32 v50, v51, v50, 1.0
	v_cvt_pk_bf16_f32 v0, v50, v0
	v_fma_f32 v50, -v54, v57, 1.0
	v_fmac_f32_e32 v57, v50, v57
	v_div_scale_f32 v50, vcc, 1.0, v53, 1.0
	v_mul_f32_e32 v51, v50, v57
	v_fma_f32 v55, -v54, v51, v50
	v_fmac_f32_e32 v51, v55, v57
	v_fma_f32 v50, -v54, v51, v50
	v_div_scale_f32 v54, s[4:5], v52, v52, 1.0
	v_rcp_f32_e32 v55, v54
	v_div_fmas_f32 v50, v50, v57, v51
	v_mul_f32_e32 v35, 0xbfb8aa3b, v35
	v_exp_f32_e32 v34, v34
	v_fma_f32 v51, -v54, v55, 1.0
	v_fmac_f32_e32 v55, v51, v55
	v_div_scale_f32 v51, vcc, 1.0, v52, 1.0
	v_exp_f32_e32 v35, v35
	v_div_fixup_f32 v50, v50, v53, 1.0
	v_mul_f32_e32 v53, v51, v55
	v_fma_f32 v56, -v54, v53, v51
	v_fmac_f32_e32 v53, v56, v55
	v_fma_f32 v51, -v54, v53, v51
	v_pk_add_f32 v[34:35], v[34:35], 1.0 op_sel_hi:[1,0]
	v_div_fmas_f32 v51, v51, v55, v53
	v_div_scale_f32 v53, s[4:5], v35, v35, 1.0
	v_rcp_f32_e32 v54, v53
	v_div_fixup_f32 v51, v51, v52, 1.0
	v_cvt_pk_bf16_f32 v50, v51, v50
	v_mov_b32_e32 v221, v0
	v_mov_b32_e32 v222, v50
	v_fma_f32 v0, -v53, v54, 1.0
	v_fmac_f32_e32 v54, v0, v54
	v_div_scale_f32 v0, vcc, 1.0, v35, 1.0
	v_mul_f32_e32 v50, v0, v54
	v_fma_f32 v51, -v53, v50, v0
	v_fmac_f32_e32 v50, v51, v54
	v_div_scale_f32 v51, s[4:5], v34, v34, 1.0
	v_rcp_f32_e32 v52, v51
	v_fma_f32 v0, -v53, v50, v0
	v_div_fmas_f32 v0, v0, v54, v50
	v_mul_f32_e32 v36, 0xbfb8aa3b, v36
	v_mul_f32_e32 v37, 0xbfb8aa3b, v37
	v_div_fixup_f32 v0, v0, v35, 1.0
	v_fma_f32 v35, -v51, v52, 1.0
	v_exp_f32_e32 v36, v36
	v_exp_f32_e32 v37, v37
	v_fmac_f32_e32 v52, v35, v52
	v_div_scale_f32 v35, vcc, 1.0, v34, 1.0
	v_mul_f32_e32 v50, v35, v52
	v_fma_f32 v53, -v51, v50, v35
	v_fmac_f32_e32 v50, v53, v52
	v_pk_add_f32 v[36:37], v[36:37], 1.0 op_sel_hi:[1,0]
	v_fma_f32 v35, -v51, v50, v35
	v_div_scale_f32 v51, s[4:5], v37, v37, 1.0
	v_rcp_f32_e32 v53, v51
	v_div_fmas_f32 v35, v35, v52, v50
	v_div_fixup_f32 v34, v35, v34, 1.0
	v_cvt_pk_bf16_f32 v0, v34, v0
	v_fma_f32 v34, -v51, v53, 1.0
	v_fmac_f32_e32 v53, v34, v53
	v_div_scale_f32 v34, vcc, 1.0, v37, 1.0
	v_mul_f32_e32 v35, v34, v53
	v_fma_f32 v50, -v51, v35, v34
	v_fmac_f32_e32 v35, v50, v53
	v_div_scale_f32 v50, s[4:5], v36, v36, 1.0
	v_fma_f32 v34, -v51, v35, v34
	v_rcp_f32_e32 v51, v50
	v_div_fmas_f32 v34, v34, v53, v35
	v_div_fixup_f32 v37, v34, v37, 1.0
	v_div_scale_f32 v52, vcc, 1.0, v36, 1.0
	v_fma_f32 v34, -v50, v51, 1.0
	v_fmac_f32_e32 v51, v34, v51
	v_mul_f32_e32 v53, v52, v51
	v_fma_f32 v34, -v50, v53, v52
	v_fmac_f32_e32 v53, v34, v51
	v_mul_f32_e32 v34, 0xbfb8aa3b, v38
	v_mul_f32_e32 v35, 0xbfb8aa3b, v39
	v_exp_f32_e32 v34, v34
	v_exp_f32_e32 v35, v35
	v_fma_f32 v38, -v50, v53, v52
	v_div_fmas_f32 v38, v38, v51, v53
	v_div_fixup_f32 v36, v38, v36, 1.0
	v_pk_add_f32 v[34:35], v[34:35], 1.0 op_sel_hi:[1,0]
	v_cvt_pk_bf16_f32 v36, v36, v37
	v_div_scale_f32 v39, s[4:5], v35, v35, 1.0
	v_rcp_f32_e32 v50, v39
	v_mov_b32_e32 v223, v0
	v_mov_b32_e32 v224, v36
	v_div_scale_f32 v38, s[4:5], v34, v34, 1.0
	v_fma_f32 v0, -v39, v50, 1.0
	v_fmac_f32_e32 v50, v0, v50
	v_div_scale_f32 v0, vcc, 1.0, v35, 1.0
	v_mul_f32_e32 v36, v0, v50
	v_fma_f32 v37, -v39, v36, v0
	v_fmac_f32_e32 v36, v37, v50
	v_fma_f32 v0, -v39, v36, v0
	v_rcp_f32_e32 v39, v38
	v_div_fmas_f32 v0, v0, v50, v36
	v_mul_f32_e32 v36, 0xbfb8aa3b, v40
	v_mul_f32_e32 v37, 0xbfb8aa3b, v41
	v_div_fixup_f32 v0, v0, v35, 1.0
	v_fma_f32 v35, -v38, v39, 1.0
	v_exp_f32_e32 v36, v36
	v_exp_f32_e32 v37, v37
	v_fmac_f32_e32 v39, v35, v39
	v_div_scale_f32 v35, vcc, 1.0, v34, 1.0
	v_mul_f32_e32 v50, v35, v39
	v_fma_f32 v40, -v38, v50, v35
	v_fmac_f32_e32 v50, v40, v39
	v_pk_add_f32 v[36:37], v[36:37], 1.0 op_sel_hi:[1,0]
	v_fma_f32 v35, -v38, v50, v35
	v_div_scale_f32 v38, s[4:5], v37, v37, 1.0
	v_rcp_f32_e32 v40, v38
	v_div_fmas_f32 v35, v35, v39, v50
	v_div_fixup_f32 v34, v35, v34, 1.0
	v_cvt_pk_bf16_f32 v0, v34, v0
	v_fma_f32 v34, -v38, v40, 1.0
	v_fmac_f32_e32 v40, v34, v40
	v_div_scale_f32 v34, vcc, 1.0, v37, 1.0
	v_mul_f32_e32 v35, v34, v40
	v_fma_f32 v39, -v38, v35, v34
	v_fmac_f32_e32 v35, v39, v40
	v_fma_f32 v34, -v38, v35, v34
	v_div_scale_f32 v38, s[4:5], v36, v36, 1.0
	v_rcp_f32_e32 v39, v38
	v_div_fmas_f32 v34, v34, v40, v35
	v_div_fixup_f32 v37, v34, v37, 1.0
	v_div_scale_f32 v40, vcc, 1.0, v36, 1.0
	v_fma_f32 v34, -v38, v39, 1.0
	v_fmac_f32_e32 v39, v34, v39
	v_mul_f32_e32 v41, v40, v39
	v_fma_f32 v34, -v38, v41, v40
	v_fmac_f32_e32 v41, v34, v39
	v_mul_f32_e32 v34, 0xbfb8aa3b, v42
	v_mul_f32_e32 v35, 0xbfb8aa3b, v43
	v_exp_f32_e32 v34, v34
	v_exp_f32_e32 v35, v35
	v_fma_f32 v38, -v38, v41, v40
	v_div_fmas_f32 v38, v38, v39, v41
	v_div_fixup_f32 v36, v38, v36, 1.0
	v_pk_add_f32 v[34:35], v[34:35], 1.0 op_sel_hi:[1,0]
	v_cvt_pk_bf16_f32 v36, v36, v37
	v_div_scale_f32 v39, s[4:5], v35, v35, 1.0
	v_rcp_f32_e32 v40, v39
	v_mov_b32_e32 v225, v0
	v_mov_b32_e32 v226, v36
	v_div_scale_f32 v38, s[4:5], v34, v34, 1.0
	v_fma_f32 v0, -v39, v40, 1.0
	v_fmac_f32_e32 v40, v0, v40
	v_div_scale_f32 v0, vcc, 1.0, v35, 1.0
	v_mul_f32_e32 v36, v0, v40
	v_fma_f32 v37, -v39, v36, v0
	v_fmac_f32_e32 v36, v37, v40
	v_fma_f32 v0, -v39, v36, v0
	v_rcp_f32_e32 v39, v38
	v_div_fmas_f32 v0, v0, v40, v36
	v_mul_f32_e32 v36, 0xbfb8aa3b, v44
	v_mul_f32_e32 v37, 0xbfb8aa3b, v45
	v_div_fixup_f32 v0, v0, v35, 1.0
	v_fma_f32 v35, -v38, v39, 1.0
	v_exp_f32_e32 v36, v36
	v_exp_f32_e32 v37, v37
	v_fmac_f32_e32 v39, v35, v39
	v_div_scale_f32 v35, vcc, 1.0, v34, 1.0
	v_mul_f32_e32 v40, v35, v39
	v_fma_f32 v41, -v38, v40, v35
	v_fmac_f32_e32 v40, v41, v39
	v_pk_add_f32 v[36:37], v[36:37], 1.0 op_sel_hi:[1,0]
	v_fma_f32 v35, -v38, v40, v35
	v_div_scale_f32 v38, s[4:5], v37, v37, 1.0
	v_rcp_f32_e32 v41, v38
	v_div_fmas_f32 v35, v35, v39, v40
	v_div_fixup_f32 v34, v35, v34, 1.0
	v_cvt_pk_bf16_f32 v0, v34, v0
	v_fma_f32 v34, -v38, v41, 1.0
	v_fmac_f32_e32 v41, v34, v41
	v_div_scale_f32 v34, vcc, 1.0, v37, 1.0
	v_mul_f32_e32 v35, v34, v41
	v_fma_f32 v39, -v38, v35, v34
	v_fmac_f32_e32 v35, v39, v41
	v_fma_f32 v34, -v38, v35, v34
	v_div_scale_f32 v38, s[4:5], v36, v36, 1.0
	v_rcp_f32_e32 v39, v38
	v_div_fmas_f32 v34, v34, v41, v35
	v_div_fixup_f32 v37, v34, v37, 1.0
	v_div_scale_f32 v40, vcc, 1.0, v36, 1.0
	v_fma_f32 v34, -v38, v39, 1.0
	v_fmac_f32_e32 v39, v34, v39
	v_mul_f32_e32 v41, v40, v39
	v_fma_f32 v34, -v38, v41, v40
	v_fmac_f32_e32 v41, v34, v39
	v_mul_f32_e32 v34, 0xbfb8aa3b, v46
	v_mul_f32_e32 v35, 0xbfb8aa3b, v47
	v_exp_f32_e32 v34, v34
	v_exp_f32_e32 v35, v35
	v_fma_f32 v38, -v38, v41, v40
	v_div_fmas_f32 v38, v38, v39, v41
	v_div_fixup_f32 v36, v38, v36, 1.0
	v_pk_add_f32 v[34:35], v[34:35], 1.0 op_sel_hi:[1,0]
	v_cvt_pk_bf16_f32 v36, v36, v37
	v_div_scale_f32 v39, s[4:5], v35, v35, 1.0
	v_rcp_f32_e32 v40, v39
	v_mov_b32_e32 v227, v0
	v_mov_b32_e32 v228, v36
	v_div_scale_f32 v38, s[4:5], v34, v34, 1.0
	v_fma_f32 v0, -v39, v40, 1.0
	v_fmac_f32_e32 v40, v0, v40
	v_div_scale_f32 v0, vcc, 1.0, v35, 1.0
	v_mul_f32_e32 v36, v0, v40
	v_fma_f32 v37, -v39, v36, v0
	v_fmac_f32_e32 v36, v37, v40
	v_fma_f32 v0, -v39, v36, v0
	v_rcp_f32_e32 v39, v38
	v_div_fmas_f32 v0, v0, v40, v36
	v_mul_f32_e32 v36, 0xbfb8aa3b, v48
	v_mul_f32_e32 v37, 0xbfb8aa3b, v49
	v_div_fixup_f32 v0, v0, v35, 1.0
	v_fma_f32 v35, -v38, v39, 1.0
	v_exp_f32_e32 v36, v36
	v_exp_f32_e32 v37, v37
	v_fmac_f32_e32 v39, v35, v39
	v_div_scale_f32 v35, vcc, 1.0, v34, 1.0
	v_mul_f32_e32 v40, v35, v39
	v_fma_f32 v41, -v38, v40, v35
	v_fmac_f32_e32 v40, v41, v39
	v_pk_add_f32 v[36:37], v[36:37], 1.0 op_sel_hi:[1,0]
	v_fma_f32 v35, -v38, v40, v35
	v_div_scale_f32 v38, s[4:5], v37, v37, 1.0
	v_rcp_f32_e32 v41, v38
	v_div_fmas_f32 v35, v35, v39, v40
	v_div_fixup_f32 v34, v35, v34, 1.0
	v_cvt_pk_bf16_f32 v0, v34, v0
	v_fma_f32 v34, -v38, v41, 1.0
	v_fmac_f32_e32 v41, v34, v41
	v_div_scale_f32 v34, vcc, 1.0, v37, 1.0
	v_mul_f32_e32 v35, v34, v41
	v_fma_f32 v39, -v38, v35, v34
	v_fmac_f32_e32 v35, v39, v41
	v_fma_f32 v34, -v38, v35, v34
	v_div_scale_f32 v38, s[4:5], v36, v36, 1.0
	v_rcp_f32_e32 v39, v38
	v_div_fmas_f32 v34, v34, v41, v35
	v_mul_f32_e32 v18, 0xbfb8aa3b, v18
	v_mul_f32_e32 v19, 0xbfb8aa3b, v19
	v_fma_f32 v35, -v38, v39, 1.0
	v_fmac_f32_e32 v39, v35, v39
	v_div_scale_f32 v35, vcc, 1.0, v36, 1.0
	v_exp_f32_e32 v18, v18
	v_exp_f32_e32 v19, v19
	v_div_fixup_f32 v34, v34, v37, 1.0
	v_mul_f32_e32 v37, v35, v39
	v_fma_f32 v40, -v38, v37, v35
	v_fmac_f32_e32 v37, v40, v39
	v_fma_f32 v35, -v38, v37, v35
	v_pk_add_f32 v[18:19], v[18:19], 1.0 op_sel_hi:[1,0]
	v_div_fmas_f32 v35, v35, v39, v37
	v_div_scale_f32 v37, s[4:5], v19, v19, 1.0
	v_rcp_f32_e32 v38, v37
	v_div_fixup_f32 v35, v35, v36, 1.0
	v_cvt_pk_bf16_f32 v34, v35, v34
	v_mov_b32_e32 v229, v0
	v_mov_b32_e32 v230, v34
	v_fma_f32 v0, -v37, v38, 1.0
	v_fmac_f32_e32 v38, v0, v38
	v_div_scale_f32 v0, vcc, 1.0, v19, 1.0
	v_mul_f32_e32 v34, v0, v38
	v_fma_f32 v35, -v37, v34, v0
	v_fmac_f32_e32 v34, v35, v38
	v_div_scale_f32 v35, s[4:5], v18, v18, 1.0
	v_rcp_f32_e32 v36, v35
	v_fma_f32 v0, -v37, v34, v0
	v_div_fmas_f32 v0, v0, v38, v34
	v_mul_f32_e32 v20, 0xbfb8aa3b, v20
	v_mul_f32_e32 v21, 0xbfb8aa3b, v21
	v_div_fixup_f32 v0, v0, v19, 1.0
	v_fma_f32 v19, -v35, v36, 1.0
	v_exp_f32_e32 v20, v20
	v_exp_f32_e32 v21, v21
	v_fmac_f32_e32 v36, v19, v36
	v_div_scale_f32 v19, vcc, 1.0, v18, 1.0
	v_mul_f32_e32 v34, v19, v36
	v_fma_f32 v37, -v35, v34, v19
	v_fmac_f32_e32 v34, v37, v36
	v_pk_add_f32 v[20:21], v[20:21], 1.0 op_sel_hi:[1,0]
	v_fma_f32 v19, -v35, v34, v19
	v_div_scale_f32 v35, s[4:5], v21, v21, 1.0
	v_rcp_f32_e32 v37, v35
	v_div_fmas_f32 v19, v19, v36, v34
	v_div_fixup_f32 v18, v19, v18, 1.0
	v_cvt_pk_bf16_f32 v0, v18, v0
	v_fma_f32 v18, -v35, v37, 1.0
	v_fmac_f32_e32 v37, v18, v37
	v_div_scale_f32 v18, vcc, 1.0, v21, 1.0
	v_mul_f32_e32 v19, v18, v37
	v_fma_f32 v34, -v35, v19, v18
	v_fmac_f32_e32 v19, v34, v37
	v_div_scale_f32 v34, s[4:5], v20, v20, 1.0
	v_fma_f32 v18, -v35, v19, v18
	v_rcp_f32_e32 v35, v34
	v_div_fmas_f32 v18, v18, v37, v19
	v_div_fixup_f32 v21, v18, v21, 1.0
	v_div_scale_f32 v36, vcc, 1.0, v20, 1.0
	v_fma_f32 v18, -v34, v35, 1.0
	v_fmac_f32_e32 v35, v18, v35
	v_mul_f32_e32 v37, v36, v35
	v_fma_f32 v18, -v34, v37, v36
	v_fmac_f32_e32 v37, v18, v35
	v_mul_f32_e32 v18, 0xbfb8aa3b, v22
	v_mul_f32_e32 v19, 0xbfb8aa3b, v23
	v_exp_f32_e32 v18, v18
	v_exp_f32_e32 v19, v19
	v_fma_f32 v22, -v34, v37, v36
	v_div_fmas_f32 v22, v22, v35, v37
	v_div_fixup_f32 v20, v22, v20, 1.0
	v_pk_add_f32 v[18:19], v[18:19], 1.0 op_sel_hi:[1,0]
	v_cvt_pk_bf16_f32 v20, v20, v21
	v_div_scale_f32 v23, s[4:5], v19, v19, 1.0
	v_rcp_f32_e32 v34, v23
	v_mov_b32_e32 v231, v0
	v_mov_b32_e32 v232, v20
	v_div_scale_f32 v22, s[4:5], v18, v18, 1.0
	v_fma_f32 v0, -v23, v34, 1.0
	v_fmac_f32_e32 v34, v0, v34
	v_div_scale_f32 v0, vcc, 1.0, v19, 1.0
	v_mul_f32_e32 v20, v0, v34
	v_fma_f32 v21, -v23, v20, v0
	v_fmac_f32_e32 v20, v21, v34
	v_fma_f32 v0, -v23, v20, v0
	v_rcp_f32_e32 v23, v22
	v_div_fmas_f32 v0, v0, v34, v20
	v_mul_f32_e32 v20, 0xbfb8aa3b, v24
	v_mul_f32_e32 v21, 0xbfb8aa3b, v25
	v_div_fixup_f32 v0, v0, v19, 1.0
	v_fma_f32 v19, -v22, v23, 1.0
	v_exp_f32_e32 v20, v20
	v_exp_f32_e32 v21, v21
	v_fmac_f32_e32 v23, v19, v23
	v_div_scale_f32 v19, vcc, 1.0, v18, 1.0
	v_mul_f32_e32 v34, v19, v23
	v_fma_f32 v24, -v22, v34, v19
	v_fmac_f32_e32 v34, v24, v23
	v_pk_add_f32 v[20:21], v[20:21], 1.0 op_sel_hi:[1,0]
	v_fma_f32 v19, -v22, v34, v19
	v_div_scale_f32 v22, s[4:5], v21, v21, 1.0
	v_rcp_f32_e32 v24, v22
	v_div_fmas_f32 v19, v19, v23, v34
	v_div_fixup_f32 v18, v19, v18, 1.0
	v_cvt_pk_bf16_f32 v0, v18, v0
	v_fma_f32 v18, -v22, v24, 1.0
	v_fmac_f32_e32 v24, v18, v24
	v_div_scale_f32 v18, vcc, 1.0, v21, 1.0
	v_mul_f32_e32 v19, v18, v24
	v_fma_f32 v23, -v22, v19, v18
	v_fmac_f32_e32 v19, v23, v24
	v_fma_f32 v18, -v22, v19, v18
	v_div_scale_f32 v22, s[4:5], v20, v20, 1.0
	v_rcp_f32_e32 v23, v22
	v_div_fmas_f32 v18, v18, v24, v19
	v_div_fixup_f32 v21, v18, v21, 1.0
	v_div_scale_f32 v24, vcc, 1.0, v20, 1.0
	v_fma_f32 v18, -v22, v23, 1.0
	v_fmac_f32_e32 v23, v18, v23
	v_mul_f32_e32 v25, v24, v23
	v_fma_f32 v18, -v22, v25, v24
	v_fmac_f32_e32 v25, v18, v23
	v_mul_f32_e32 v18, 0xbfb8aa3b, v26
	v_mul_f32_e32 v19, 0xbfb8aa3b, v27
	v_exp_f32_e32 v18, v18
	v_exp_f32_e32 v19, v19
	v_fma_f32 v22, -v22, v25, v24
	v_div_fmas_f32 v22, v22, v23, v25
	v_div_fixup_f32 v20, v22, v20, 1.0
	v_pk_add_f32 v[18:19], v[18:19], 1.0 op_sel_hi:[1,0]
	v_cvt_pk_bf16_f32 v20, v20, v21
	v_div_scale_f32 v23, s[4:5], v19, v19, 1.0
	v_rcp_f32_e32 v24, v23
	v_mov_b32_e32 v233, v0
	v_mov_b32_e32 v234, v20
	v_div_scale_f32 v22, s[4:5], v18, v18, 1.0
	v_fma_f32 v0, -v23, v24, 1.0
	v_fmac_f32_e32 v24, v0, v24
	v_div_scale_f32 v0, vcc, 1.0, v19, 1.0
	v_mul_f32_e32 v20, v0, v24
	v_fma_f32 v21, -v23, v20, v0
	v_fmac_f32_e32 v20, v21, v24
	v_fma_f32 v0, -v23, v20, v0
	v_rcp_f32_e32 v23, v22
	v_div_fmas_f32 v0, v0, v24, v20
	v_mul_f32_e32 v20, 0xbfb8aa3b, v28
	v_mul_f32_e32 v21, 0xbfb8aa3b, v29
	v_div_fixup_f32 v0, v0, v19, 1.0
	v_fma_f32 v19, -v22, v23, 1.0
	v_exp_f32_e32 v20, v20
	v_exp_f32_e32 v21, v21
	v_fmac_f32_e32 v23, v19, v23
	v_div_scale_f32 v19, vcc, 1.0, v18, 1.0
	v_mul_f32_e32 v24, v19, v23
	v_fma_f32 v25, -v22, v24, v19
	v_fmac_f32_e32 v24, v25, v23
	v_pk_add_f32 v[20:21], v[20:21], 1.0 op_sel_hi:[1,0]
	v_fma_f32 v19, -v22, v24, v19
	v_div_scale_f32 v22, s[4:5], v21, v21, 1.0
	v_rcp_f32_e32 v25, v22
	v_div_fmas_f32 v19, v19, v23, v24
	v_div_fixup_f32 v18, v19, v18, 1.0
	v_cvt_pk_bf16_f32 v0, v18, v0
	v_fma_f32 v18, -v22, v25, 1.0
	v_fmac_f32_e32 v25, v18, v25
	v_div_scale_f32 v18, vcc, 1.0, v21, 1.0
	v_mul_f32_e32 v19, v18, v25
	v_fma_f32 v23, -v22, v19, v18
	v_fmac_f32_e32 v19, v23, v25
	v_fma_f32 v18, -v22, v19, v18
	v_div_scale_f32 v22, s[4:5], v20, v20, 1.0
	v_rcp_f32_e32 v23, v22
	v_div_fmas_f32 v18, v18, v25, v19
	v_div_fixup_f32 v21, v18, v21, 1.0
	v_div_scale_f32 v24, vcc, 1.0, v20, 1.0
	v_fma_f32 v18, -v22, v23, 1.0
	v_fmac_f32_e32 v23, v18, v23
	v_mul_f32_e32 v25, v24, v23
	v_fma_f32 v18, -v22, v25, v24
	v_fmac_f32_e32 v25, v18, v23
	v_mul_f32_e32 v18, 0xbfb8aa3b, v30
	v_mul_f32_e32 v19, 0xbfb8aa3b, v31
	v_exp_f32_e32 v18, v18
	v_exp_f32_e32 v19, v19
	v_fma_f32 v22, -v22, v25, v24
	v_div_fmas_f32 v22, v22, v23, v25
	v_div_fixup_f32 v20, v22, v20, 1.0
	v_pk_add_f32 v[18:19], v[18:19], 1.0 op_sel_hi:[1,0]
	v_cvt_pk_bf16_f32 v20, v20, v21
	v_div_scale_f32 v23, s[4:5], v19, v19, 1.0
	v_rcp_f32_e32 v24, v23
	v_mov_b32_e32 v235, v0
	v_mov_b32_e32 v174, v20
	v_div_scale_f32 v22, s[4:5], v18, v18, 1.0
	v_fma_f32 v0, -v23, v24, 1.0
	v_fmac_f32_e32 v24, v0, v24
	v_div_scale_f32 v0, vcc, 1.0, v19, 1.0
	v_mul_f32_e32 v20, v0, v24
	v_fma_f32 v21, -v23, v20, v0
	v_fmac_f32_e32 v20, v21, v24
	v_fma_f32 v0, -v23, v20, v0
	v_rcp_f32_e32 v23, v22
	v_div_fmas_f32 v0, v0, v24, v20
	v_mul_f32_e32 v20, 0xbfb8aa3b, v32
	v_mul_f32_e32 v21, 0xbfb8aa3b, v33
	v_div_fixup_f32 v0, v0, v19, 1.0
	v_fma_f32 v19, -v22, v23, 1.0
	v_exp_f32_e32 v20, v20
	v_exp_f32_e32 v21, v21
	v_fmac_f32_e32 v23, v19, v23
	v_div_scale_f32 v19, vcc, 1.0, v18, 1.0
	v_mul_f32_e32 v24, v19, v23
	v_fma_f32 v25, -v22, v24, v19
	v_fmac_f32_e32 v24, v25, v23
	v_pk_add_f32 v[20:21], v[20:21], 1.0 op_sel_hi:[1,0]
	v_fma_f32 v19, -v22, v24, v19
	v_div_scale_f32 v22, s[4:5], v21, v21, 1.0
	v_rcp_f32_e32 v25, v22
	v_div_fmas_f32 v19, v19, v23, v24
	v_div_fixup_f32 v18, v19, v18, 1.0
	v_cvt_pk_bf16_f32 v0, v18, v0
	v_fma_f32 v18, -v22, v25, 1.0
	v_fmac_f32_e32 v25, v18, v25
	v_div_scale_f32 v18, vcc, 1.0, v21, 1.0
	v_mul_f32_e32 v19, v18, v25
	v_fma_f32 v23, -v22, v19, v18
	v_fmac_f32_e32 v19, v23, v25
	v_fma_f32 v18, -v22, v19, v18
	v_div_scale_f32 v22, s[4:5], v20, v20, 1.0
	v_rcp_f32_e32 v23, v22
	v_div_fmas_f32 v18, v18, v25, v19
	v_mul_f32_e32 v2, 0xbfb8aa3b, v2
	v_mul_f32_e32 v3, 0xbfb8aa3b, v3
	v_fma_f32 v19, -v22, v23, 1.0
	v_fmac_f32_e32 v23, v19, v23
	v_div_scale_f32 v19, vcc, 1.0, v20, 1.0
	v_exp_f32_e32 v2, v2
	v_exp_f32_e32 v3, v3
	v_div_fixup_f32 v18, v18, v21, 1.0
	v_mul_f32_e32 v21, v19, v23
	v_fma_f32 v24, -v22, v21, v19
	v_fmac_f32_e32 v21, v24, v23
	v_fma_f32 v19, -v22, v21, v19
	v_pk_add_f32 v[2:3], v[2:3], 1.0 op_sel_hi:[1,0]
	v_div_fmas_f32 v19, v19, v23, v21
	v_div_scale_f32 v21, s[4:5], v3, v3, 1.0
	v_rcp_f32_e32 v22, v21
	v_div_fixup_f32 v19, v19, v20, 1.0
	v_cvt_pk_bf16_f32 v18, v19, v18
	v_mov_b32_e32 v175, v0
	v_mov_b32_e32 v176, v18
	v_fma_f32 v0, -v21, v22, 1.0
	v_fmac_f32_e32 v22, v0, v22
	v_div_scale_f32 v0, vcc, 1.0, v3, 1.0
	v_mul_f32_e32 v18, v0, v22
	v_fma_f32 v19, -v21, v18, v0
	v_fmac_f32_e32 v18, v19, v22
	v_div_scale_f32 v19, s[4:5], v2, v2, 1.0
	v_rcp_f32_e32 v20, v19
	v_fma_f32 v0, -v21, v18, v0
	v_div_fmas_f32 v0, v0, v22, v18
	v_mul_f32_e32 v4, 0xbfb8aa3b, v4
	v_mul_f32_e32 v5, 0xbfb8aa3b, v5
	v_div_fixup_f32 v0, v0, v3, 1.0
	v_fma_f32 v3, -v19, v20, 1.0
	v_exp_f32_e32 v4, v4
	v_exp_f32_e32 v5, v5
	v_fmac_f32_e32 v20, v3, v20
	v_div_scale_f32 v3, vcc, 1.0, v2, 1.0
	v_mul_f32_e32 v18, v3, v20
	v_fma_f32 v21, -v19, v18, v3
	v_fmac_f32_e32 v18, v21, v20
	v_pk_add_f32 v[4:5], v[4:5], 1.0 op_sel_hi:[1,0]
	v_fma_f32 v3, -v19, v18, v3
	v_div_scale_f32 v19, s[4:5], v5, v5, 1.0
	v_rcp_f32_e32 v21, v19
	v_div_fmas_f32 v3, v3, v20, v18
	v_div_fixup_f32 v2, v3, v2, 1.0
	v_cvt_pk_bf16_f32 v0, v2, v0
	v_fma_f32 v2, -v19, v21, 1.0
	v_fmac_f32_e32 v21, v2, v21
	v_div_scale_f32 v2, vcc, 1.0, v5, 1.0
	v_mul_f32_e32 v3, v2, v21
	v_fma_f32 v18, -v19, v3, v2
	v_fmac_f32_e32 v3, v18, v21
	v_div_scale_f32 v18, s[4:5], v4, v4, 1.0
	v_fma_f32 v2, -v19, v3, v2
	v_rcp_f32_e32 v19, v18
	v_div_fmas_f32 v2, v2, v21, v3
	v_div_fixup_f32 v5, v2, v5, 1.0
	v_div_scale_f32 v20, vcc, 1.0, v4, 1.0
	v_fma_f32 v2, -v18, v19, 1.0
	v_fmac_f32_e32 v19, v2, v19
	v_mul_f32_e32 v21, v20, v19
	v_fma_f32 v2, -v18, v21, v20
	v_fmac_f32_e32 v21, v2, v19
	v_mul_f32_e32 v2, 0xbfb8aa3b, v6
	v_mul_f32_e32 v3, 0xbfb8aa3b, v7
	v_exp_f32_e32 v2, v2
	v_exp_f32_e32 v3, v3
	v_fma_f32 v6, -v18, v21, v20
	v_div_fmas_f32 v6, v6, v19, v21
	v_div_fixup_f32 v4, v6, v4, 1.0
	v_pk_add_f32 v[2:3], v[2:3], 1.0 op_sel_hi:[1,0]
	v_cvt_pk_bf16_f32 v4, v4, v5
	v_div_scale_f32 v7, s[4:5], v3, v3, 1.0
	v_rcp_f32_e32 v18, v7
	v_mov_b32_e32 v177, v0
	v_mov_b32_e32 v178, v4
	v_div_scale_f32 v6, s[4:5], v2, v2, 1.0
	v_fma_f32 v0, -v7, v18, 1.0
	v_fmac_f32_e32 v18, v0, v18
	v_div_scale_f32 v0, vcc, 1.0, v3, 1.0
	v_mul_f32_e32 v4, v0, v18
	v_fma_f32 v5, -v7, v4, v0
	v_fmac_f32_e32 v4, v5, v18
	v_fma_f32 v0, -v7, v4, v0
	v_rcp_f32_e32 v7, v6
	v_div_fmas_f32 v0, v0, v18, v4
	v_mul_f32_e32 v4, 0xbfb8aa3b, v8
	v_mul_f32_e32 v5, 0xbfb8aa3b, v9
	v_div_fixup_f32 v0, v0, v3, 1.0
	v_fma_f32 v3, -v6, v7, 1.0
	v_exp_f32_e32 v4, v4
	v_exp_f32_e32 v5, v5
	v_fmac_f32_e32 v7, v3, v7
	v_div_scale_f32 v3, vcc, 1.0, v2, 1.0
	v_mul_f32_e32 v18, v3, v7
	v_fma_f32 v8, -v6, v18, v3
	v_fmac_f32_e32 v18, v8, v7
	v_pk_add_f32 v[4:5], v[4:5], 1.0 op_sel_hi:[1,0]
	v_fma_f32 v3, -v6, v18, v3
	v_div_scale_f32 v6, s[4:5], v5, v5, 1.0
	v_rcp_f32_e32 v8, v6
	v_div_fmas_f32 v3, v3, v7, v18
	v_div_fixup_f32 v2, v3, v2, 1.0
	v_cvt_pk_bf16_f32 v0, v2, v0
	v_fma_f32 v2, -v6, v8, 1.0
	v_fmac_f32_e32 v8, v2, v8
	v_div_scale_f32 v2, vcc, 1.0, v5, 1.0
	v_mul_f32_e32 v3, v2, v8
	v_fma_f32 v7, -v6, v3, v2
	v_fmac_f32_e32 v3, v7, v8
	v_fma_f32 v2, -v6, v3, v2
	v_div_scale_f32 v6, s[4:5], v4, v4, 1.0
	v_rcp_f32_e32 v7, v6
	v_div_fmas_f32 v2, v2, v8, v3
	v_div_fixup_f32 v5, v2, v5, 1.0
	v_div_scale_f32 v8, vcc, 1.0, v4, 1.0
	v_fma_f32 v2, -v6, v7, 1.0
	v_fmac_f32_e32 v7, v2, v7
	v_mul_f32_e32 v9, v8, v7
	v_fma_f32 v2, -v6, v9, v8
	v_fmac_f32_e32 v9, v2, v7
	v_mul_f32_e32 v2, 0xbfb8aa3b, v10
	v_mul_f32_e32 v3, 0xbfb8aa3b, v11
	v_exp_f32_e32 v2, v2
	v_exp_f32_e32 v3, v3
	v_fma_f32 v6, -v6, v9, v8
	v_div_fmas_f32 v6, v6, v7, v9
	v_div_fixup_f32 v4, v6, v4, 1.0
	v_pk_add_f32 v[2:3], v[2:3], 1.0 op_sel_hi:[1,0]
	v_cvt_pk_bf16_f32 v4, v4, v5
	v_div_scale_f32 v7, s[4:5], v3, v3, 1.0
	v_rcp_f32_e32 v8, v7
	v_mov_b32_e32 v179, v0
	v_mov_b32_e32 v180, v4
	v_div_scale_f32 v6, s[4:5], v2, v2, 1.0
	v_fma_f32 v0, -v7, v8, 1.0
	v_fmac_f32_e32 v8, v0, v8
	v_div_scale_f32 v0, vcc, 1.0, v3, 1.0
	v_mul_f32_e32 v4, v0, v8
	v_fma_f32 v5, -v7, v4, v0
	v_fmac_f32_e32 v4, v5, v8
	v_fma_f32 v0, -v7, v4, v0
	v_rcp_f32_e32 v7, v6
	v_div_fmas_f32 v0, v0, v8, v4
	v_mul_f32_e32 v4, 0xbfb8aa3b, v12
	v_mul_f32_e32 v5, 0xbfb8aa3b, v13
	v_div_fixup_f32 v0, v0, v3, 1.0
	v_fma_f32 v3, -v6, v7, 1.0
	v_exp_f32_e32 v4, v4
	v_exp_f32_e32 v5, v5
	v_fmac_f32_e32 v7, v3, v7
	v_div_scale_f32 v3, vcc, 1.0, v2, 1.0
	v_mul_f32_e32 v8, v3, v7
	v_fma_f32 v9, -v6, v8, v3
	v_fmac_f32_e32 v8, v9, v7
	v_pk_add_f32 v[4:5], v[4:5], 1.0 op_sel_hi:[1,0]
	v_fma_f32 v3, -v6, v8, v3
	v_div_scale_f32 v6, s[4:5], v5, v5, 1.0
	v_rcp_f32_e32 v9, v6
	v_div_fmas_f32 v3, v3, v7, v8
	v_div_fixup_f32 v2, v3, v2, 1.0
	v_cvt_pk_bf16_f32 v0, v2, v0
	v_fma_f32 v2, -v6, v9, 1.0
	v_fmac_f32_e32 v9, v2, v9
	v_div_scale_f32 v2, vcc, 1.0, v5, 1.0
	v_mul_f32_e32 v3, v2, v9
	v_fma_f32 v7, -v6, v3, v2
	v_fmac_f32_e32 v3, v7, v9
	v_fma_f32 v2, -v6, v3, v2
	v_div_scale_f32 v6, s[4:5], v4, v4, 1.0
	v_rcp_f32_e32 v7, v6
	v_div_fmas_f32 v2, v2, v9, v3
	v_div_fixup_f32 v5, v2, v5, 1.0
	v_div_scale_f32 v8, vcc, 1.0, v4, 1.0
	v_fma_f32 v2, -v6, v7, 1.0
	v_fmac_f32_e32 v7, v2, v7
	v_mul_f32_e32 v9, v8, v7
	v_fma_f32 v2, -v6, v9, v8
	v_fmac_f32_e32 v9, v2, v7
	v_mul_f32_e32 v2, 0xbfb8aa3b, v14
	v_mul_f32_e32 v3, 0xbfb8aa3b, v15
	v_exp_f32_e32 v2, v2
	v_exp_f32_e32 v3, v3
	v_fma_f32 v6, -v6, v9, v8
	v_div_fmas_f32 v6, v6, v7, v9
	v_div_fixup_f32 v4, v6, v4, 1.0
	v_pk_add_f32 v[2:3], v[2:3], 1.0 op_sel_hi:[1,0]
	v_cvt_pk_bf16_f32 v4, v4, v5
	v_div_scale_f32 v7, s[4:5], v3, v3, 1.0
	v_rcp_f32_e32 v8, v7
	v_mov_b32_e32 v181, v0
	v_mov_b32_e32 v182, v4
	v_div_scale_f32 v6, s[4:5], v2, v2, 1.0
	v_fma_f32 v0, -v7, v8, 1.0
	v_fmac_f32_e32 v8, v0, v8
	v_div_scale_f32 v0, vcc, 1.0, v3, 1.0
	v_mul_f32_e32 v4, v0, v8
	v_fma_f32 v5, -v7, v4, v0
	v_fmac_f32_e32 v4, v5, v8
	v_fma_f32 v0, -v7, v4, v0
	v_rcp_f32_e32 v7, v6
	v_div_fmas_f32 v0, v0, v8, v4
	v_mul_f32_e32 v4, 0xbfb8aa3b, v16
	v_mul_f32_e32 v5, 0xbfb8aa3b, v17
	v_div_fixup_f32 v0, v0, v3, 1.0
	v_fma_f32 v3, -v6, v7, 1.0
	v_exp_f32_e32 v4, v4
	v_exp_f32_e32 v5, v5
	v_fmac_f32_e32 v7, v3, v7
	v_div_scale_f32 v3, vcc, 1.0, v2, 1.0
	v_mul_f32_e32 v8, v3, v7
	v_fma_f32 v9, -v6, v8, v3
	v_fmac_f32_e32 v8, v9, v7
	v_pk_add_f32 v[4:5], v[4:5], 1.0 op_sel_hi:[1,0]
	v_fma_f32 v3, -v6, v8, v3
	v_div_scale_f32 v6, s[4:5], v5, v5, 1.0
	v_rcp_f32_e32 v9, v6
	v_div_fmas_f32 v3, v3, v7, v8
	v_div_fixup_f32 v2, v3, v2, 1.0
	v_cvt_pk_bf16_f32 v0, v2, v0
	v_fma_f32 v2, -v6, v9, 1.0
	v_fmac_f32_e32 v9, v2, v9
	v_div_scale_f32 v2, vcc, 1.0, v5, 1.0
	v_mul_f32_e32 v3, v2, v9
	v_fma_f32 v7, -v6, v3, v2
	v_fmac_f32_e32 v3, v7, v9
	v_fma_f32 v2, -v6, v3, v2
	v_div_scale_f32 v6, s[4:5], v4, v4, 1.0
	v_rcp_f32_e32 v7, v6
	v_div_fmas_f32 v2, v2, v9, v3
	v_div_fixup_f32 v2, v2, v5, 1.0
	s_or_b32 s4, s6, s13
	v_fma_f32 v3, -v6, v7, 1.0
	v_fmac_f32_e32 v7, v3, v7
	v_div_scale_f32 v3, vcc, 1.0, v4, 1.0
	v_mul_f32_e32 v5, v3, v7
	v_fma_f32 v8, -v6, v5, v3
	v_fmac_f32_e32 v5, v8, v7
	v_fma_f32 v3, -v6, v5, v3
	v_div_fmas_f32 v3, v3, v7, v5
	v_div_fixup_f32 v3, v3, v4, 1.0
	v_cvt_pk_bf16_f32 v2, v3, v2
	v_mov_b32_e32 v3, v133
	v_mov_b32_e32 v183, v0
	v_mov_b32_e32 v213, v2
	s_mov_b32 s15, 0xfffffc0
	v_lshlrev_b32_e32 v0, 3, v3
	v_ashrrev_i32_e32 v4, 3, v3
	v_and_b32_e32 v156, 56, v0
	v_add_u32_e32 v0, 0x100, v3
	v_ashrrev_i32_e32 v5, 3, v0
	v_add_u32_e32 v6, 0x200, v3
	v_mul_lo_u32 v4, v4, s21
	v_ashrrev_i32_e32 v6, 3, v6
	v_add_u32_e32 v7, 0x300, v3
	v_mul_lo_u32 v4, v5, s21
	v_ashrrev_i32_e32 v7, 3, v7
	v_mul_lo_u32 v4, v6, s21
	v_mul_lo_u32 v4, v7, s21
	v_and_b32_e32 v2, 31, v3
	v_add_lshl_u32 v214, v4, v156, 1
	v_lshrrev_b32_e32 v4, 1, v3
	s_add_u32 s4, s42, s4
	v_and_or_b32 v5, v4, s15, v2
	v_and_b32_e32 v2, 16, v4
	s_addc_u32 s5, s43, 0
	s_lshl_b32 s6, s12, 10
	v_mad_u64_u32 v[158:159], s[16:17], v5, s37, v[2:3]
	v_and_b32_e32 v3, 0x5f, v3
	s_add_u32 s6, s9, s6
	v_mad_u32_u24 v159, v3, s37, v2
	v_mov_b32_e32 v2, 0
	s_mov_b32 s14, 1
	s_addc_u32 s7, s10, 0
	v_or_b32_e32 v162, v174, v156
	v_or_b32_e32 v160, v175, v156
	v_or_b32_e32 v0, v176, v156
	v_or_b32_e32 v164, v177, v156
	v_or_b32_e32 v166, v178, v156
	v_or_b32_e32 v168, v179, v156
	v_or_b32_e32 v170, v180, v156
	v_or_b32_e32 v172, v181, v156
	v_mov_b32_e32 v3, v2
	v_mov_b32_e32 v4, v2
	v_mov_b32_e32 v5, v2
	v_mov_b32_e32 v6, v2
	v_mov_b32_e32 v7, v2
	v_mov_b32_e32 v8, v2
	v_mov_b32_e32 v9, v2
	v_mov_b32_e32 v10, v2
	v_mov_b32_e32 v11, v2
	v_mov_b32_e32 v12, v2
	v_mov_b32_e32 v13, v2
	v_mov_b32_e32 v14, v2
	v_mov_b32_e32 v15, v2
	v_mov_b32_e32 v16, v2
	v_mov_b32_e32 v17, v2
	v_mov_b32_e32 v18, v2
	v_mov_b32_e32 v19, v2
	v_mov_b32_e32 v20, v2
	v_mov_b32_e32 v21, v2
	v_mov_b32_e32 v22, v2
	v_mov_b32_e32 v23, v2
	v_mov_b32_e32 v24, v2
	v_mov_b32_e32 v25, v2
	v_mov_b32_e32 v26, v2
	v_mov_b32_e32 v27, v2
	v_mov_b32_e32 v28, v2
	v_mov_b32_e32 v29, v2
	v_mov_b32_e32 v30, v2
	v_mov_b32_e32 v31, v2
	v_mov_b32_e32 v32, v2
	v_mov_b32_e32 v33, v2
	v_mov_b32_e32 v34, v2
	v_mov_b32_e32 v35, v2
	v_mov_b32_e32 v36, v2
	v_mov_b32_e32 v37, v2
	v_mov_b32_e32 v38, v2
	v_mov_b32_e32 v39, v2
	v_mov_b32_e32 v40, v2
	v_mov_b32_e32 v41, v2
	v_mov_b32_e32 v42, v2
	v_mov_b32_e32 v43, v2
	v_mov_b32_e32 v44, v2
	v_mov_b32_e32 v45, v2
	v_mov_b32_e32 v46, v2
	v_mov_b32_e32 v47, v2
	v_mov_b32_e32 v48, v2
	v_mov_b32_e32 v49, v2
	v_mov_b32_e32 v50, v2
	v_mov_b32_e32 v51, v2
	v_mov_b32_e32 v52, v2
	v_mov_b32_e32 v53, v2
	v_mov_b32_e32 v54, v2
	v_mov_b32_e32 v55, v2
	v_mov_b32_e32 v56, v2
	v_mov_b32_e32 v57, v2
	v_mov_b32_e32 v58, v2
	v_mov_b32_e32 v59, v2
	v_mov_b32_e32 v60, v2
	v_mov_b32_e32 v61, v2
	v_mov_b32_e32 v62, v2
	v_mov_b32_e32 v63, v2
	v_mov_b32_e32 v64, v2
	v_mov_b32_e32 v65, v2
	v_and_b32_e32 v236, 63, v133
	v_lshrrev_b32_e32 v237, 6, v133
	v_lshlrev_b32_e32 v238, 12, v237
	v_lshrrev_b32_e32 v239, 3, v236
	v_readfirstlane_b32 s15, v238
	v_lshl_add_u32 v239, v237, 5, v239
	v_and_b32_e32 v240, 7, v236
	v_lshrrev_b32_e32 v241, 4, v236
	v_xor_b32_e32 v240, v240, v241
	v_xor_b32_e32 v241, 4, v240
	v_lshlrev_b32_e32 v240, 4, v240
	v_lshlrev_b32_e32 v241, 4, v241
	v_mul_u32_u24_e32 v242, 0xc00, v239
	v_lshlrev_b32_e32 v243, 10, v239
	v_add_u32_e32 v158, v242, v240
	v_add_u32_e32 v159, v242, v241
	v_add_u32_e32 v159, 0x6000, v159
	v_add_u32_e32 v160, 0xc000, v158
	v_add_u32_e32 v161, 0xc000, v159
	v_add_u32_e32 v162, v243, v240
	v_add_u32_e32 v163, v243, v241
	v_add_u32_e32 v163, 0x2000, v163
	v_add_u32_e32 v164, 0x4000, v162
	v_add_u32_e32 v165, 0x4000, v163
	v_and_b32_e32 v238, 31, v236
	v_lshrrev_b32_e32 v239, 5, v236
	v_bfe_u32 v240, v236, 1, 3
	v_xor_b32_e32 v239, v239, v240
	v_lshrrev_b32_e32 v240, 1, v237
	v_and_b32_e32 v241, 1, v237
	v_lshl_add_u32 v240, v240, 6, v238
	v_lshl_add_u32 v241, v241, 6, v238
	v_lshlrev_b32_e32 v240, 7, v240
	v_lshlrev_b32_e32 v241, 7, v241
	v_add_u32_e32 v241, 0x4000, v241
	v_lshl_add_u32 v166, v239, 4, v240
	v_lshl_add_u32 v170, v239, 4, v241
	v_xor_b32_e32 v242, 2, v239
	v_lshl_add_u32 v167, v242, 4, v240
	v_lshl_add_u32 v171, v242, 4, v241
	v_xor_b32_e32 v242, 4, v239
	v_lshl_add_u32 v168, v242, 4, v240
	v_lshl_add_u32 v172, v242, 4, v241
	v_xor_b32_e32 v242, 6, v239
	v_lshl_add_u32 v169, v242, 4, v240
	v_lshl_add_u32 v173, v242, 4, v241
	s_waitcnt lgkmcnt(0)
	s_barrier
	s_add_u32 m0, s15, 0x0
	s_nop 0
	global_load_lds_dwordx4 v158, s[6:7]
	s_add_u32 m0, s15, 0x400
	s_nop 0
	global_load_lds_dwordx4 v159, s[6:7]
	s_add_u32 m0, s15, 0x800
	s_nop 0
	global_load_lds_dwordx4 v160, s[6:7]
	s_add_u32 m0, s15, 0xc00
	s_nop 0
	global_load_lds_dwordx4 v161, s[6:7]
	s_add_u32 m0, s15, 0x4000
	s_nop 0
	global_load_lds_dwordx4 v162, s[4:5]
	s_add_u32 m0, s15, 0x4400
	s_nop 0
	global_load_lds_dwordx4 v163, s[4:5]
	s_add_u32 m0, s15, 0x4800
	s_nop 0
	global_load_lds_dwordx4 v164, s[4:5]
	s_add_u32 m0, s15, 0x4c00
	s_nop 0
	global_load_lds_dwordx4 v165, s[4:5]
	v_add_u32_e32 v158, 0x80, v158
	v_add_u32_e32 v159, 0x80, v159
	v_add_u32_e32 v160, 0x80, v160
	v_add_u32_e32 v161, 0x80, v161
	v_add_u32_e32 v162, 0x80, v162
	v_add_u32_e32 v163, 0x80, v163
	v_add_u32_e32 v164, 0x80, v164
	v_add_u32_e32 v165, 0x80, v165
	s_mov_b32 s14, 0
	s_waitcnt vmcnt(0)
.Lmgu_loop:
	s_barrier
	s_add_u32 m0, s15, 0x8000
	s_nop 0
	global_load_lds_dwordx4 v158, s[6:7]
	s_add_u32 m0, s15, 0x8400
	s_nop 0
	global_load_lds_dwordx4 v159, s[6:7]
	s_add_u32 m0, s15, 0x8800
	s_nop 0
	global_load_lds_dwordx4 v160, s[6:7]
	s_add_u32 m0, s15, 0x8c00
	s_nop 0
	global_load_lds_dwordx4 v161, s[6:7]
	s_add_u32 m0, s15, 0xc000
	s_nop 0
	global_load_lds_dwordx4 v162, s[4:5]
	s_add_u32 m0, s15, 0xc400
	s_nop 0
	global_load_lds_dwordx4 v163, s[4:5]
	s_add_u32 m0, s15, 0xc800
	s_nop 0
	global_load_lds_dwordx4 v164, s[4:5]
	s_add_u32 m0, s15, 0xcc00
	s_nop 0
	global_load_lds_dwordx4 v165, s[4:5]
	v_add_u32_e32 v158, 0x80, v158
	v_add_u32_e32 v159, 0x80, v159
	v_add_u32_e32 v160, 0x80, v160
	v_add_u32_e32 v161, 0x80, v161
	v_add_u32_e32 v162, 0x80, v162
	v_add_u32_e32 v163, 0x80, v163
	v_add_u32_e32 v164, 0x80, v164
	v_add_u32_e32 v165, 0x80, v165
	ds_read_b128 v[236:239], v166
	ds_read_b128 v[244:247], v170
	ds_read_b128 v[248:251], v170 offset:4096
	ds_read_b128 v[240:243], v166 offset:4096
	s_waitcnt lgkmcnt(2)
	v_mfma_f32_32x32x16_bf16 v[50:65], v[236:239], v[244:247], v[50:65]
	s_waitcnt lgkmcnt(1)
	v_mfma_f32_32x32x16_bf16 v[34:49], v[236:239], v[248:251], v[34:49]
	ds_read_b128 v[236:239], v167
	s_waitcnt lgkmcnt(1)
	v_mfma_f32_32x32x16_bf16 v[18:33], v[240:243], v[244:247], v[18:33]
	ds_read_b128 v[244:247], v171
	v_mfma_f32_32x32x16_bf16 v[2:17], v[240:243], v[248:251], v[2:17]
	ds_read_b128 v[248:251], v171 offset:4096
	ds_read_b128 v[240:243], v167 offset:4096
	s_waitcnt lgkmcnt(2)
	v_mfma_f32_32x32x16_bf16 v[50:65], v[236:239], v[244:247], v[50:65]
	s_waitcnt lgkmcnt(1)
	v_mfma_f32_32x32x16_bf16 v[34:49], v[236:239], v[248:251], v[34:49]
	ds_read_b128 v[236:239], v168
	s_waitcnt lgkmcnt(1)
	v_mfma_f32_32x32x16_bf16 v[18:33], v[240:243], v[244:247], v[18:33]
	ds_read_b128 v[244:247], v172
	v_mfma_f32_32x32x16_bf16 v[2:17], v[240:243], v[248:251], v[2:17]
	ds_read_b128 v[248:251], v172 offset:4096
	ds_read_b128 v[240:243], v168 offset:4096
	s_waitcnt lgkmcnt(2)
	v_mfma_f32_32x32x16_bf16 v[50:65], v[236:239], v[244:247], v[50:65]
	s_waitcnt lgkmcnt(1)
	v_mfma_f32_32x32x16_bf16 v[34:49], v[236:239], v[248:251], v[34:49]
	ds_read_b128 v[236:239], v169
	s_waitcnt lgkmcnt(1)
	v_mfma_f32_32x32x16_bf16 v[18:33], v[240:243], v[244:247], v[18:33]
	ds_read_b128 v[244:247], v173
	v_mfma_f32_32x32x16_bf16 v[2:17], v[240:243], v[248:251], v[2:17]
	ds_read_b128 v[248:251], v173 offset:4096
	ds_read_b128 v[240:243], v169 offset:4096
	s_waitcnt lgkmcnt(2)
	v_mfma_f32_32x32x16_bf16 v[50:65], v[236:239], v[244:247], v[50:65]
	s_waitcnt lgkmcnt(1)
	v_mfma_f32_32x32x16_bf16 v[34:49], v[236:239], v[248:251], v[34:49]
	s_waitcnt lgkmcnt(0)
	v_mfma_f32_32x32x16_bf16 v[18:33], v[240:243], v[244:247], v[18:33]
	v_mfma_f32_32x32x16_bf16 v[2:17], v[240:243], v[248:251], v[2:17]
	s_waitcnt vmcnt(0)
	s_barrier
	s_cmp_eq_u32 s14, 3
	s_cbranch_scc1 .Lmgu_skip
	s_add_u32 m0, s15, 0x0
	s_nop 0
	global_load_lds_dwordx4 v158, s[6:7]
	s_add_u32 m0, s15, 0x400
	s_nop 0
	global_load_lds_dwordx4 v159, s[6:7]
	s_add_u32 m0, s15, 0x800
	s_nop 0
	global_load_lds_dwordx4 v160, s[6:7]
	s_add_u32 m0, s15, 0xc00
	s_nop 0
	global_load_lds_dwordx4 v161, s[6:7]
	s_add_u32 m0, s15, 0x4000
	s_nop 0
	global_load_lds_dwordx4 v162, s[4:5]
	s_add_u32 m0, s15, 0x4400
	s_nop 0
	global_load_lds_dwordx4 v163, s[4:5]
	s_add_u32 m0, s15, 0x4800
	s_nop 0
	global_load_lds_dwordx4 v164, s[4:5]
	s_add_u32 m0, s15, 0x4c00
	s_nop 0
	global_load_lds_dwordx4 v165, s[4:5]
	v_add_u32_e32 v158, 0x80, v158
	v_add_u32_e32 v159, 0x80, v159
	v_add_u32_e32 v160, 0x80, v160
	v_add_u32_e32 v161, 0x80, v161
	v_add_u32_e32 v162, 0x80, v162
	v_add_u32_e32 v163, 0x80, v163
	v_add_u32_e32 v164, 0x80, v164
	v_add_u32_e32 v165, 0x80, v165
.Lmgu_skip:
	ds_read_b128 v[236:239], v166 offset:32768
	ds_read_b128 v[244:247], v170 offset:32768
	ds_read_b128 v[248:251], v170 offset:36864
	ds_read_b128 v[240:243], v166 offset:36864
	s_waitcnt lgkmcnt(2)
	v_mfma_f32_32x32x16_bf16 v[50:65], v[236:239], v[244:247], v[50:65]
	s_waitcnt lgkmcnt(1)
	v_mfma_f32_32x32x16_bf16 v[34:49], v[236:239], v[248:251], v[34:49]
	ds_read_b128 v[236:239], v167 offset:32768
	s_waitcnt lgkmcnt(1)
	v_mfma_f32_32x32x16_bf16 v[18:33], v[240:243], v[244:247], v[18:33]
	ds_read_b128 v[244:247], v171 offset:32768
	v_mfma_f32_32x32x16_bf16 v[2:17], v[240:243], v[248:251], v[2:17]
	ds_read_b128 v[248:251], v171 offset:36864
	ds_read_b128 v[240:243], v167 offset:36864
	s_waitcnt lgkmcnt(2)
	v_mfma_f32_32x32x16_bf16 v[50:65], v[236:239], v[244:247], v[50:65]
	s_waitcnt lgkmcnt(1)
	v_mfma_f32_32x32x16_bf16 v[34:49], v[236:239], v[248:251], v[34:49]
	ds_read_b128 v[236:239], v168 offset:32768
	s_waitcnt lgkmcnt(1)
	v_mfma_f32_32x32x16_bf16 v[18:33], v[240:243], v[244:247], v[18:33]
	ds_read_b128 v[244:247], v172 offset:32768
	v_mfma_f32_32x32x16_bf16 v[2:17], v[240:243], v[248:251], v[2:17]
	ds_read_b128 v[248:251], v172 offset:36864
	ds_read_b128 v[240:243], v168 offset:36864
	s_waitcnt lgkmcnt(2)
	v_mfma_f32_32x32x16_bf16 v[50:65], v[236:239], v[244:247], v[50:65]
	s_waitcnt lgkmcnt(1)
	v_mfma_f32_32x32x16_bf16 v[34:49], v[236:239], v[248:251], v[34:49]
	ds_read_b128 v[236:239], v169 offset:32768
	s_waitcnt lgkmcnt(1)
	v_mfma_f32_32x32x16_bf16 v[18:33], v[240:243], v[244:247], v[18:33]
	ds_read_b128 v[244:247], v173 offset:32768
	v_mfma_f32_32x32x16_bf16 v[2:17], v[240:243], v[248:251], v[2:17]
	ds_read_b128 v[248:251], v173 offset:36864
	ds_read_b128 v[240:243], v169 offset:36864
	s_waitcnt lgkmcnt(2)
	v_mfma_f32_32x32x16_bf16 v[50:65], v[236:239], v[244:247], v[50:65]
	s_waitcnt lgkmcnt(1)
	v_mfma_f32_32x32x16_bf16 v[34:49], v[236:239], v[248:251], v[34:49]
	s_waitcnt lgkmcnt(0)
	v_mfma_f32_32x32x16_bf16 v[18:33], v[240:243], v[244:247], v[18:33]
	v_mfma_f32_32x32x16_bf16 v[2:17], v[240:243], v[248:251], v[2:17]
	s_waitcnt vmcnt(0)
	s_add_i32 s14, s14, 1
	s_cmp_lg_u32 s14, 4
	s_cbranch_scc1 .Lmgu_loop
	s_nop 15
	v_mov_b32_e32 v158, v215
	v_mov_b32_e32 v159, v216
	s_add_i32 s12, s12, 1
	s_cmp_lg_u32 s12, 3
	s_waitcnt lgkmcnt(0)
	v_lshlrev_b32_e32 v160, 16, v158
	v_and_b32_e32 v161, 0xffff0000, v158
	v_pk_fma_f32 v[128:129], v[50:51], v[160:161], v[128:129]
	v_lshlrev_b32_e32 v50, 16, v159
	v_and_b32_e32 v51, 0xffff0000, v159
	v_pk_fma_f32 v[126:127], v[52:53], v[50:51], v[126:127]
	v_mov_b32_e32 v50, v217
	v_mov_b32_e32 v51, v218
	s_waitcnt lgkmcnt(0)
	v_lshlrev_b32_e32 v52, 16, v50
	v_and_b32_e32 v53, 0xffff0000, v50
	v_lshlrev_b32_e32 v50, 16, v51
	v_and_b32_e32 v51, 0xffff0000, v51
	v_pk_fma_f32 v[118:119], v[56:57], v[50:51], v[118:119]
	v_mov_b32_e32 v50, v219
	v_mov_b32_e32 v51, v220
	v_pk_fma_f32 v[122:123], v[54:55], v[52:53], v[122:123]
	s_waitcnt lgkmcnt(0)
	v_lshlrev_b32_e32 v52, 16, v50
	v_and_b32_e32 v53, 0xffff0000, v50
	v_lshlrev_b32_e32 v50, 16, v51
	v_and_b32_e32 v51, 0xffff0000, v51
	v_pk_fma_f32 v[110:111], v[60:61], v[50:51], v[110:111]
	v_mov_b32_e32 v50, v221
	v_mov_b32_e32 v51, v222
	v_pk_fma_f32 v[114:115], v[58:59], v[52:53], v[114:115]
	s_waitcnt lgkmcnt(0)
	v_lshlrev_b32_e32 v52, 16, v50
	v_and_b32_e32 v53, 0xffff0000, v50
	v_lshlrev_b32_e32 v50, 16, v51
	v_and_b32_e32 v51, 0xffff0000, v51
	v_pk_fma_f32 v[100:101], v[64:65], v[50:51], v[100:101]
	v_mov_b32_e32 v50, v223
	v_mov_b32_e32 v51, v224
	v_pk_fma_f32 v[106:107], v[62:63], v[52:53], v[106:107]
	s_waitcnt lgkmcnt(0)
	v_lshlrev_b32_e32 v52, 16, v50
	v_and_b32_e32 v53, 0xffff0000, v50
	v_pk_fma_f32 v[124:125], v[34:35], v[52:53], v[124:125]
	v_lshlrev_b32_e32 v34, 16, v51
	v_and_b32_e32 v35, 0xffff0000, v51
	v_pk_fma_f32 v[120:121], v[36:37], v[34:35], v[120:121]
	v_mov_b32_e32 v34, v225
	v_mov_b32_e32 v35, v226
	s_waitcnt lgkmcnt(0)
	v_lshlrev_b32_e32 v36, 16, v34
	v_and_b32_e32 v37, 0xffff0000, v34
	v_lshlrev_b32_e32 v34, 16, v35
	v_and_b32_e32 v35, 0xffff0000, v35
	v_pk_fma_f32 v[112:113], v[40:41], v[34:35], v[112:113]
	v_mov_b32_e32 v34, v227
	v_mov_b32_e32 v35, v228
	v_pk_fma_f32 v[116:117], v[38:39], v[36:37], v[116:117]
	s_waitcnt lgkmcnt(0)
	v_lshlrev_b32_e32 v36, 16, v34
	v_and_b32_e32 v37, 0xffff0000, v34
	v_lshlrev_b32_e32 v34, 16, v35
	v_and_b32_e32 v35, 0xffff0000, v35
	v_pk_fma_f32 v[104:105], v[44:45], v[34:35], v[104:105]
	v_mov_b32_e32 v34, v229
	v_mov_b32_e32 v35, v230
	v_pk_fma_f32 v[108:109], v[42:43], v[36:37], v[108:109]
	s_waitcnt lgkmcnt(0)
	v_lshlrev_b32_e32 v36, 16, v34
	v_and_b32_e32 v37, 0xffff0000, v34
	v_lshlrev_b32_e32 v34, 16, v35
	v_and_b32_e32 v35, 0xffff0000, v35
	v_pk_fma_f32 v[98:99], v[48:49], v[34:35], v[98:99]
	v_mov_b32_e32 v34, v231
	v_mov_b32_e32 v35, v232
	v_pk_fma_f32 v[102:103], v[46:47], v[36:37], v[102:103]
	s_waitcnt lgkmcnt(0)
	v_lshlrev_b32_e32 v36, 16, v34
	v_and_b32_e32 v37, 0xffff0000, v34
	v_pk_fma_f32 v[96:97], v[18:19], v[36:37], v[96:97]
	v_lshlrev_b32_e32 v18, 16, v35
	v_and_b32_e32 v19, 0xffff0000, v35
	v_pk_fma_f32 v[94:95], v[20:21], v[18:19], v[94:95]
	v_mov_b32_e32 v18, v233
	v_mov_b32_e32 v19, v234
	s_waitcnt lgkmcnt(0)
	v_lshlrev_b32_e32 v20, 16, v18
	v_and_b32_e32 v21, 0xffff0000, v18
	v_lshlrev_b32_e32 v18, 16, v19
	v_and_b32_e32 v19, 0xffff0000, v19
	v_pk_fma_f32 v[86:87], v[24:25], v[18:19], v[86:87]
	v_mov_b32_e32 v18, v235
	v_mov_b32_e32 v19, v174
	v_pk_fma_f32 v[90:91], v[22:23], v[20:21], v[90:91]
	s_waitcnt lgkmcnt(0)
	v_lshlrev_b32_e32 v20, 16, v18
	v_and_b32_e32 v21, 0xffff0000, v18
	v_lshlrev_b32_e32 v18, 16, v19
	v_and_b32_e32 v19, 0xffff0000, v19
	v_pk_fma_f32 v[78:79], v[28:29], v[18:19], v[78:79]
	v_mov_b32_e32 v18, v175
	v_mov_b32_e32 v19, v176
	v_pk_fma_f32 v[82:83], v[26:27], v[20:21], v[82:83]
	s_waitcnt lgkmcnt(0)
	v_lshlrev_b32_e32 v20, 16, v18
	v_and_b32_e32 v21, 0xffff0000, v18
	v_lshlrev_b32_e32 v18, 16, v19
	v_and_b32_e32 v19, 0xffff0000, v19
	v_pk_fma_f32 v[68:69], v[32:33], v[18:19], v[68:69]
	v_mov_b32_e32 v18, v177
	v_mov_b32_e32 v19, v178
	v_pk_fma_f32 v[74:75], v[30:31], v[20:21], v[74:75]
	s_waitcnt lgkmcnt(0)
	v_lshlrev_b32_e32 v20, 16, v18
	v_and_b32_e32 v21, 0xffff0000, v18
	v_pk_fma_f32 v[92:93], v[2:3], v[20:21], v[92:93]
	v_lshlrev_b32_e32 v2, 16, v19
	v_and_b32_e32 v3, 0xffff0000, v19
	v_pk_fma_f32 v[88:89], v[4:5], v[2:3], v[88:89]
	v_mov_b32_e32 v2, v179
	v_mov_b32_e32 v3, v180
	s_waitcnt lgkmcnt(0)
	v_lshlrev_b32_e32 v4, 16, v2
	v_and_b32_e32 v5, 0xffff0000, v2
	v_lshlrev_b32_e32 v2, 16, v3
	v_and_b32_e32 v3, 0xffff0000, v3
	v_pk_fma_f32 v[80:81], v[8:9], v[2:3], v[80:81]
	v_mov_b32_e32 v2, v181
	v_mov_b32_e32 v3, v182
	v_pk_fma_f32 v[84:85], v[6:7], v[4:5], v[84:85]
	s_waitcnt lgkmcnt(0)
	v_lshlrev_b32_e32 v4, 16, v2
	v_and_b32_e32 v5, 0xffff0000, v2
	v_lshlrev_b32_e32 v2, 16, v3
	v_and_b32_e32 v3, 0xffff0000, v3
	v_pk_fma_f32 v[72:73], v[12:13], v[2:3], v[72:73]
	v_mov_b32_e32 v2, v183
	v_mov_b32_e32 v3, v213
	v_pk_fma_f32 v[76:77], v[10:11], v[4:5], v[76:77]
	s_waitcnt lgkmcnt(0)
	v_lshlrev_b32_e32 v4, 16, v2
	v_and_b32_e32 v5, 0xffff0000, v2
	v_lshlrev_b32_e32 v2, 16, v3
	v_and_b32_e32 v3, 0xffff0000, v3
	v_pk_fma_f32 v[70:71], v[14:15], v[4:5], v[70:71]
	v_pk_fma_f32 v[66:67], v[16:17], v[2:3], v[66:67]
	s_cbranch_scc1 .LBB0_105
	v_mov_b32_e32 v0, v133
	v_mov_b32_e32 v2, v133
	s_nop 0
	v_and_b32_e32 v3, 64, v2
	v_and_b32_e32 v5, 31, v0
	v_ashrrev_i32_e32 v2, 1, v2
	v_lshrrev_b32_e32 v0, 3, v0
	v_and_b32_e32 v2, 0xffffffc0, v2
	v_and_or_b32 v0, v0, 4, s96
	v_add_u32_e32 v4, v0, v2
	v_or3_b32 v0, v5, v3, s8
	v_lshlrev_b32_e32 v0, 1, v0
	v_ashrrev_i32_e32 v5, 31, v4
	v_lshl_add_u64 v[2:3], s[88:89], 0, v[0:1]
	v_lshlrev_b64 v[6:7], 11, v[4:5]
	v_cvt_pk_bf16_f32 v0, v128, s0
	v_lshl_add_u64 v[6:7], v[2:3], 0, v[6:7]
	global_store_short v[6:7], v0, off
	v_cvt_pk_bf16_f32 v0, v124, s0
	global_store_short v[6:7], v0, off offset:64
	v_or_b32_e32 v6, 1, v4
	v_ashrrev_i32_e32 v7, 31, v6
	v_lshlrev_b64 v[6:7], 11, v[6:7]
	v_cvt_pk_bf16_f32 v0, v129, s0
	v_lshl_add_u64 v[6:7], v[2:3], 0, v[6:7]
	global_store_short v[6:7], v0, off
	v_cvt_pk_bf16_f32 v0, v125, s0
	global_store_short v[6:7], v0, off offset:64
	v_or_b32_e32 v6, 2, v4
	v_ashrrev_i32_e32 v7, 31, v6
	v_lshlrev_b64 v[6:7], 11, v[6:7]
	v_cvt_pk_bf16_f32 v0, v126, s0
	v_lshl_add_u64 v[6:7], v[2:3], 0, v[6:7]
	global_store_short v[6:7], v0, off
	v_cvt_pk_bf16_f32 v0, v120, s0
	global_store_short v[6:7], v0, off offset:64
	v_or_b32_e32 v6, 3, v4
	v_ashrrev_i32_e32 v7, 31, v6
	v_lshlrev_b64 v[6:7], 11, v[6:7]
	v_cvt_pk_bf16_f32 v0, v127, s0
	v_lshl_add_u64 v[6:7], v[2:3], 0, v[6:7]
	global_store_short v[6:7], v0, off
	v_cvt_pk_bf16_f32 v0, v121, s0
	global_store_short v[6:7], v0, off offset:64
	v_or_b32_e32 v6, 8, v4
	v_ashrrev_i32_e32 v7, 31, v6
	v_lshlrev_b64 v[6:7], 11, v[6:7]
	v_cvt_pk_bf16_f32 v0, v122, s0
	v_lshl_add_u64 v[6:7], v[2:3], 0, v[6:7]
	global_store_short v[6:7], v0, off
	v_cvt_pk_bf16_f32 v0, v116, s0
	global_store_short v[6:7], v0, off offset:64
	v_or_b32_e32 v6, 9, v4
	v_ashrrev_i32_e32 v7, 31, v6
	v_lshlrev_b64 v[6:7], 11, v[6:7]
	v_cvt_pk_bf16_f32 v0, v123, s0
	v_lshl_add_u64 v[6:7], v[2:3], 0, v[6:7]
	global_store_short v[6:7], v0, off
	v_cvt_pk_bf16_f32 v0, v117, s0
	global_store_short v[6:7], v0, off offset:64
	v_or_b32_e32 v6, 10, v4
	v_ashrrev_i32_e32 v7, 31, v6
	v_lshlrev_b64 v[6:7], 11, v[6:7]
	v_cvt_pk_bf16_f32 v0, v118, s0
	v_lshl_add_u64 v[6:7], v[2:3], 0, v[6:7]
	global_store_short v[6:7], v0, off
	v_cvt_pk_bf16_f32 v0, v112, s0
	global_store_short v[6:7], v0, off offset:64
	v_or_b32_e32 v6, 11, v4
	v_ashrrev_i32_e32 v7, 31, v6
	v_lshlrev_b64 v[6:7], 11, v[6:7]
	v_cvt_pk_bf16_f32 v0, v119, s0
	v_lshl_add_u64 v[6:7], v[2:3], 0, v[6:7]
	global_store_short v[6:7], v0, off
	v_cvt_pk_bf16_f32 v0, v113, s0
	global_store_short v[6:7], v0, off offset:64
	v_or_b32_e32 v6, 16, v4
	v_ashrrev_i32_e32 v7, 31, v6
	v_lshlrev_b64 v[6:7], 11, v[6:7]
	v_cvt_pk_bf16_f32 v0, v114, s0
	v_lshl_add_u64 v[6:7], v[2:3], 0, v[6:7]
	global_store_short v[6:7], v0, off
	v_cvt_pk_bf16_f32 v0, v108, s0
	global_store_short v[6:7], v0, off offset:64
	v_or_b32_e32 v6, 17, v4
	v_ashrrev_i32_e32 v7, 31, v6
	v_lshlrev_b64 v[6:7], 11, v[6:7]
	v_cvt_pk_bf16_f32 v0, v115, s0
	v_lshl_add_u64 v[6:7], v[2:3], 0, v[6:7]
	global_store_short v[6:7], v0, off
	v_cvt_pk_bf16_f32 v0, v109, s0
	global_store_short v[6:7], v0, off offset:64
	v_or_b32_e32 v6, 18, v4
	v_ashrrev_i32_e32 v7, 31, v6
	v_lshlrev_b64 v[6:7], 11, v[6:7]
	v_cvt_pk_bf16_f32 v0, v110, s0
	v_lshl_add_u64 v[6:7], v[2:3], 0, v[6:7]
	global_store_short v[6:7], v0, off
	v_cvt_pk_bf16_f32 v0, v104, s0
	global_store_short v[6:7], v0, off offset:64
	v_or_b32_e32 v6, 19, v4
	v_ashrrev_i32_e32 v7, 31, v6
	v_lshlrev_b64 v[6:7], 11, v[6:7]
	v_cvt_pk_bf16_f32 v0, v111, s0
	v_lshl_add_u64 v[6:7], v[2:3], 0, v[6:7]
	global_store_short v[6:7], v0, off
	v_cvt_pk_bf16_f32 v0, v105, s0
	global_store_short v[6:7], v0, off offset:64
	v_or_b32_e32 v6, 24, v4
	v_ashrrev_i32_e32 v7, 31, v6
	v_lshlrev_b64 v[6:7], 11, v[6:7]
	v_cvt_pk_bf16_f32 v0, v106, s0
	v_lshl_add_u64 v[6:7], v[2:3], 0, v[6:7]
	global_store_short v[6:7], v0, off
	v_cvt_pk_bf16_f32 v0, v102, s0
	global_store_short v[6:7], v0, off offset:64
	v_or_b32_e32 v6, 25, v4
	v_ashrrev_i32_e32 v7, 31, v6
	v_lshlrev_b64 v[6:7], 11, v[6:7]
	v_cvt_pk_bf16_f32 v0, v107, s0
	v_lshl_add_u64 v[6:7], v[2:3], 0, v[6:7]
	global_store_short v[6:7], v0, off
	v_cvt_pk_bf16_f32 v0, v103, s0
	global_store_short v[6:7], v0, off offset:64
	v_or_b32_e32 v6, 26, v4
	v_ashrrev_i32_e32 v7, 31, v6
	v_lshlrev_b64 v[6:7], 11, v[6:7]
	v_cvt_pk_bf16_f32 v0, v100, s0
	v_lshl_add_u64 v[6:7], v[2:3], 0, v[6:7]
	global_store_short v[6:7], v0, off
	v_cvt_pk_bf16_f32 v0, v98, s0
	global_store_short v[6:7], v0, off offset:64
	v_or_b32_e32 v6, 27, v4
	v_ashrrev_i32_e32 v7, 31, v6
	v_lshlrev_b64 v[6:7], 11, v[6:7]
	v_cvt_pk_bf16_f32 v0, v101, s0
	v_lshl_add_u64 v[6:7], v[2:3], 0, v[6:7]
	global_store_short v[6:7], v0, off
	v_cvt_pk_bf16_f32 v0, v99, s0
	global_store_short v[6:7], v0, off offset:64
	v_or_b32_e32 v6, 32, v4
	v_ashrrev_i32_e32 v7, 31, v6
	v_lshlrev_b64 v[6:7], 11, v[6:7]
	v_cvt_pk_bf16_f32 v0, v96, s0
	v_lshl_add_u64 v[6:7], v[2:3], 0, v[6:7]
	global_store_short v[6:7], v0, off
	v_cvt_pk_bf16_f32 v0, v92, s0
	global_store_short v[6:7], v0, off offset:64
	v_or_b32_e32 v6, 33, v4
	v_ashrrev_i32_e32 v7, 31, v6
	v_lshlrev_b64 v[6:7], 11, v[6:7]
	v_cvt_pk_bf16_f32 v0, v97, s0
	v_lshl_add_u64 v[6:7], v[2:3], 0, v[6:7]
	global_store_short v[6:7], v0, off
	v_cvt_pk_bf16_f32 v0, v93, s0
	global_store_short v[6:7], v0, off offset:64
	v_or_b32_e32 v6, 34, v4
	v_ashrrev_i32_e32 v7, 31, v6
	v_lshlrev_b64 v[6:7], 11, v[6:7]
	v_cvt_pk_bf16_f32 v0, v94, s0
	v_lshl_add_u64 v[6:7], v[2:3], 0, v[6:7]
	global_store_short v[6:7], v0, off
	v_cvt_pk_bf16_f32 v0, v88, s0
	global_store_short v[6:7], v0, off offset:64
	v_or_b32_e32 v6, 35, v4
	v_ashrrev_i32_e32 v7, 31, v6
	v_lshlrev_b64 v[6:7], 11, v[6:7]
	v_cvt_pk_bf16_f32 v0, v95, s0
	v_lshl_add_u64 v[6:7], v[2:3], 0, v[6:7]
	global_store_short v[6:7], v0, off
	v_cvt_pk_bf16_f32 v0, v89, s0
	global_store_short v[6:7], v0, off offset:64
	v_or_b32_e32 v6, 40, v4
	v_ashrrev_i32_e32 v7, 31, v6
	v_lshlrev_b64 v[6:7], 11, v[6:7]
	v_cvt_pk_bf16_f32 v0, v90, s0
	v_lshl_add_u64 v[6:7], v[2:3], 0, v[6:7]
	global_store_short v[6:7], v0, off
	v_cvt_pk_bf16_f32 v0, v84, s0
	global_store_short v[6:7], v0, off offset:64
	v_or_b32_e32 v6, 41, v4
	v_ashrrev_i32_e32 v7, 31, v6
	v_lshlrev_b64 v[6:7], 11, v[6:7]
	v_cvt_pk_bf16_f32 v0, v91, s0
	v_lshl_add_u64 v[6:7], v[2:3], 0, v[6:7]
	global_store_short v[6:7], v0, off
	v_cvt_pk_bf16_f32 v0, v85, s0
	global_store_short v[6:7], v0, off offset:64
	v_or_b32_e32 v6, 42, v4
	v_ashrrev_i32_e32 v7, 31, v6
	v_lshlrev_b64 v[6:7], 11, v[6:7]
	v_cvt_pk_bf16_f32 v0, v86, s0
	v_lshl_add_u64 v[6:7], v[2:3], 0, v[6:7]
	global_store_short v[6:7], v0, off
	v_cvt_pk_bf16_f32 v0, v80, s0
	global_store_short v[6:7], v0, off offset:64
	v_or_b32_e32 v6, 43, v4
	v_ashrrev_i32_e32 v7, 31, v6
	v_lshlrev_b64 v[6:7], 11, v[6:7]
	v_cvt_pk_bf16_f32 v0, v87, s0
	v_lshl_add_u64 v[6:7], v[2:3], 0, v[6:7]
	global_store_short v[6:7], v0, off
	v_cvt_pk_bf16_f32 v0, v81, s0
	global_store_short v[6:7], v0, off offset:64
	v_or_b32_e32 v6, 48, v4
	v_ashrrev_i32_e32 v7, 31, v6
	v_lshlrev_b64 v[6:7], 11, v[6:7]
	v_cvt_pk_bf16_f32 v0, v82, s0
	v_lshl_add_u64 v[6:7], v[2:3], 0, v[6:7]
	global_store_short v[6:7], v0, off
	v_cvt_pk_bf16_f32 v0, v76, s0
	global_store_short v[6:7], v0, off offset:64
	v_or_b32_e32 v6, 49, v4
	v_ashrrev_i32_e32 v7, 31, v6
	v_lshlrev_b64 v[6:7], 11, v[6:7]
	v_cvt_pk_bf16_f32 v0, v83, s0
	v_lshl_add_u64 v[6:7], v[2:3], 0, v[6:7]
	global_store_short v[6:7], v0, off
	v_cvt_pk_bf16_f32 v0, v77, s0
	global_store_short v[6:7], v0, off offset:64
	v_or_b32_e32 v6, 50, v4
	v_ashrrev_i32_e32 v7, 31, v6
	v_lshlrev_b64 v[6:7], 11, v[6:7]
	v_cvt_pk_bf16_f32 v0, v78, s0
	v_lshl_add_u64 v[6:7], v[2:3], 0, v[6:7]
	global_store_short v[6:7], v0, off
	v_cvt_pk_bf16_f32 v0, v72, s0
	global_store_short v[6:7], v0, off offset:64
	v_or_b32_e32 v6, 51, v4
	v_ashrrev_i32_e32 v7, 31, v6
	v_lshlrev_b64 v[6:7], 11, v[6:7]
	v_cvt_pk_bf16_f32 v0, v79, s0
	v_lshl_add_u64 v[6:7], v[2:3], 0, v[6:7]
	global_store_short v[6:7], v0, off
	v_cvt_pk_bf16_f32 v0, v73, s0
	global_store_short v[6:7], v0, off offset:64
	v_or_b32_e32 v6, 56, v4
	v_ashrrev_i32_e32 v7, 31, v6
	v_lshlrev_b64 v[6:7], 11, v[6:7]
	v_cvt_pk_bf16_f32 v0, v74, s0
	v_lshl_add_u64 v[6:7], v[2:3], 0, v[6:7]
	global_store_short v[6:7], v0, off
	v_cvt_pk_bf16_f32 v0, v70, s0
	global_store_short v[6:7], v0, off offset:64
	v_or_b32_e32 v6, 57, v4
	v_ashrrev_i32_e32 v7, 31, v6
	v_lshlrev_b64 v[6:7], 11, v[6:7]
	v_cvt_pk_bf16_f32 v0, v75, s0
	v_lshl_add_u64 v[6:7], v[2:3], 0, v[6:7]
	global_store_short v[6:7], v0, off
	v_cvt_pk_bf16_f32 v0, v71, s0
	global_store_short v[6:7], v0, off offset:64
	v_or_b32_e32 v6, 58, v4
	v_ashrrev_i32_e32 v7, 31, v6
	v_lshlrev_b64 v[6:7], 11, v[6:7]
	v_or_b32_e32 v4, 59, v4
	v_cvt_pk_bf16_f32 v0, v68, s0
	v_lshl_add_u64 v[6:7], v[2:3], 0, v[6:7]
	v_ashrrev_i32_e32 v5, 31, v4
	global_store_short v[6:7], v0, off
	v_cvt_pk_bf16_f32 v0, v66, s0
	v_lshlrev_b64 v[4:5], 11, v[4:5]
	global_store_short v[6:7], v0, off offset:64
	v_cvt_pk_bf16_f32 v0, v69, s0
	v_lshl_add_u64 v[2:3], v[2:3], 0, v[4:5]
	global_store_short v[2:3], v0, off
	v_cvt_pk_bf16_f32 v0, v67, s0
	global_store_short v[2:3], v0, off offset:64
	v_mov_b32_e32 v0, v133
	s_waitcnt vmcnt(63) expcnt(7) lgkmcnt(15)
	s_barrier
	s_nop 0
	v_cmp_eq_u32_e32 vcc, 0, v0
	s_and_saveexec_b64 s[4:5], vcc
	s_cbranch_execz .LBB0_103
	s_mov_b64 s[8:9], 0
	s_branch .LBB0_114
